# prep job: 16-lane shuffle butterflies (qk-norm sum, rope partner exchange) via DPP row ops instead of ds_bpermute round trips
# speedup vs baseline: 1.0004x; 1.0004x over previous
.Lprepa_norope2:
	s_waitcnt vmcnt(0)
	v_lshlrev_b32_e32 v8, 16, v12
	v_and_b32_e32 v9, 0xffff0000, v12
	v_lshlrev_b32_e32 v10, 16, v13
	v_and_b32_e32 v11, 0xffff0000, v13
	v_pk_mul_f32 v[24:25], v[8:9], v[8:9]
	v_pk_mul_f32 v[26:27], v[10:11], v[10:11]
	v_add_f32_e32 v24, v24, v25
	v_lshlrev_b32_e32 v12, 16, v14
	v_and_b32_e32 v13, 0xffff0000, v14
	v_add_f32_e32 v24, v24, v26
	v_pk_mul_f32 v[30:31], v[12:13], v[12:13]
	v_add_f32_e32 v24, v27, v24
	v_lshlrev_b32_e32 v14, 16, v15
	v_and_b32_e32 v15, 0xffff0000, v15
	v_add_f32_e32 v24, v30, v24
	v_pk_mul_f32 v[32:33], v[14:15], v[14:15]
	v_add_f32_e32 v24, v31, v24
	v_add_f32_e32 v24, v32, v24
	v_add_f32_e32 v24, v33, v24
	s_nop 1
	s_waitcnt lgkmcnt(0)
	v_add_f32_dpp v24, v24, v24 quad_perm:[1,0,3,2] row_mask:0xf bank_mask:0xf
	s_nop 1
	s_waitcnt lgkmcnt(0)
	v_add_f32_dpp v24, v24, v24 quad_perm:[2,3,0,1] row_mask:0xf bank_mask:0xf
	s_nop 1
	v_mov_b32_dpp v25, v24 row_shl:4 row_mask:0xf bank_mask:0x5
	v_mov_b32_dpp v25, v24 row_shr:4 row_mask:0xf bank_mask:0xa
	s_waitcnt lgkmcnt(0)
	v_add_f32_e32 v25, v24, v25
	s_nop 1
	v_mov_b32_dpp v26, v25 row_ror:8 row_mask:0xf bank_mask:0xf
	v_lshlrev_b32_e32 v24, 2, v16
	s_and_saveexec_b64 s[58:59], s[0:1]
	s_cbranch_execz .LBB0_303
	s_waitcnt lgkmcnt(0)
	v_add_f32_e32 v25, v25, v26
	v_fmamk_f32 v25, v25, 0x3c000000, v115
	v_cmp_gt_f32_e64 s[0:1], s78, v25
	v_mul_f32_e32 v26, 0x4b800000, v25
	v_mov_b32_e32 v27, s21
	v_cndmask_b32_e64 v25, v25, v26, s[0:1]
	v_rsq_f32_e32 v25, v25
	s_nop 0
	v_mul_f32_e32 v26, 0x45800000, v25
	v_cndmask_b32_e64 v26, v25, v26, s[0:1]
	v_mov_b32_e32 v25, s3
	v_cndmask_b32_e64 v31, v25, v27, s[12:13]
	v_mov_b32_e32 v25, s2
	v_mov_b32_e32 v27, s20
	v_cndmask_b32_e64 v30, v25, v27, s[12:13]
	v_mov_b32_e32 v25, v113
	v_lshl_add_u64 v[34:35], v[30:31], 0, v[24:25]
	v_mov_b32_e32 v30, v130
	v_mov_b32_e32 v31, v131
	v_mov_b32_e32 v32, v132
	v_mov_b32_e32 v33, v133
	v_mov_b32_e32 v48, v134
	v_mov_b32_e32 v49, v135
	v_mov_b32_e32 v50, v136
	v_mov_b32_e32 v51, v137
	v_pk_mul_f32 v[32:33], v[26:27], v[32:33] op_sel_hi:[0,1]
	v_pk_mul_f32 v[34:35], v[26:27], v[50:51] op_sel_hi:[0,1]
	v_pk_mul_f32 v[30:31], v[26:27], v[30:31] op_sel_hi:[0,1]
	v_pk_mul_f32 v[26:27], v[26:27], v[48:49] op_sel_hi:[0,1]
	v_pk_mul_f32 v[14:15], v[34:35], v[14:15]
	v_pk_mul_f32 v[10:11], v[32:33], v[10:11]
	v_pk_mul_f32 v[12:13], v[26:27], v[12:13]
	v_pk_mul_f32 v[8:9], v[30:31], v[8:9]
.LBB0_303:
	s_or_b64 exec, exec, s[58:59]
	s_nop 1
	v_mov_b32_dpp v34, v8 row_shl:4 row_mask:0xf bank_mask:0x5
	v_mov_b32_dpp v34, v8 row_shr:4 row_mask:0xf bank_mask:0xa
	s_nop 1
	v_mov_b32_dpp v35, v9 row_shl:4 row_mask:0xf bank_mask:0x5
	v_mov_b32_dpp v35, v9 row_shr:4 row_mask:0xf bank_mask:0xa
	s_nop 1
	v_mov_b32_dpp v32, v10 row_shl:4 row_mask:0xf bank_mask:0x5
	v_mov_b32_dpp v32, v10 row_shr:4 row_mask:0xf bank_mask:0xa
	s_nop 1
	v_mov_b32_dpp v33, v11 row_shl:4 row_mask:0xf bank_mask:0x5
	v_mov_b32_dpp v33, v11 row_shr:4 row_mask:0xf bank_mask:0xa
	s_nop 1
	v_mov_b32_dpp v30, v12 row_shl:4 row_mask:0xf bank_mask:0x5
	v_mov_b32_dpp v30, v12 row_shr:4 row_mask:0xf bank_mask:0xa
	s_nop 1
	v_mov_b32_dpp v31, v13 row_shl:4 row_mask:0xf bank_mask:0x5
	v_mov_b32_dpp v31, v13 row_shr:4 row_mask:0xf bank_mask:0xa
	s_nop 1
	v_mov_b32_dpp v47, v14 row_shl:4 row_mask:0xf bank_mask:0x5
	v_mov_b32_dpp v47, v14 row_shr:4 row_mask:0xf bank_mask:0xa
	s_nop 1
	v_mov_b32_dpp v25, v15 row_shl:4 row_mask:0xf bank_mask:0x5
	v_mov_b32_dpp v25, v15 row_shr:4 row_mask:0xf bank_mask:0xa
	v_and_b32_e32 v28, s55, v46
	s_and_b64 s[58:59], vcc, s[10:11]
	s_waitcnt lgkmcnt(8)
	v_lshlrev_b32_e32 v26, 9, v28
	s_and_saveexec_b64 s[0:1], s[58:59]
	s_cbranch_execz .LBB0_305
	v_mov_b32_e32 v27, v113
	v_lshl_add_u64 v[60:61], v[20:21], 0, v[26:27]
	v_mov_b32_e32 v48, v138
	v_mov_b32_e32 v49, v139
	v_mov_b32_e32 v50, v140
	v_mov_b32_e32 v51, v141
	v_mov_b32_e32 v52, v142
	v_mov_b32_e32 v53, v143
	v_mov_b32_e32 v54, v144
	v_mov_b32_e32 v55, v145
	v_mov_b32_e32 v56, v146
	v_mov_b32_e32 v57, v147
	v_mov_b32_e32 v58, v148
	v_mov_b32_e32 v59, v149
	v_mov_b32_e32 v60, v150
	v_mov_b32_e32 v61, v151
	v_mov_b32_e32 v62, v152
	v_mov_b32_e32 v63, v153
	s_waitcnt lgkmcnt(6)
	v_pk_mul_f32 v[34:35], v[18:19], v[34:35]
	s_waitcnt lgkmcnt(4)
	v_pk_mul_f32 v[32:33], v[18:19], v[32:33]
	s_waitcnt lgkmcnt(2)
	v_pk_mul_f32 v[30:31], v[18:19], v[30:31]
	s_waitcnt lgkmcnt(1)
	v_mul_f32_e32 v27, v18, v47
	s_nop 0
	v_mul_f32_e32 v14, v14, v48
	v_mul_f32_e32 v48, v27, v49
	s_nop 0
	v_mov_b32_e32 v64, v60
	v_mov_b32_e32 v65, v62
	v_mov_b32_e32 v62, v61
	v_mov_b32_e32 v60, v56
	v_mov_b32_e32 v61, v58
	v_mov_b32_e32 v58, v57
	v_mov_b32_e32 v56, v52
	v_mov_b32_e32 v57, v54
	v_mov_b32_e32 v54, v53
	s_waitcnt lgkmcnt(0)
	v_mul_f32_e32 v53, v18, v25
	v_mov_b32_e32 v52, v15
	v_pk_mul_f32 v[50:51], v[52:53], v[50:51]
	v_pk_mul_f32 v[34:35], v[34:35], v[62:63]
	v_pk_mul_f32 v[32:33], v[32:33], v[58:59]
	v_pk_mul_f32 v[30:31], v[30:31], v[54:55]
	v_mov_b32_e32 v15, v50
	v_mov_b32_e32 v49, v51
	v_pk_fma_f32 v[8:9], v[8:9], v[64:65], v[34:35]
	v_pk_fma_f32 v[10:11], v[10:11], v[60:61], v[32:33]
	v_pk_fma_f32 v[12:13], v[12:13], v[56:57], v[30:31]
	v_pk_add_f32 v[14:15], v[14:15], v[48:49]

.LBB0_317:
	s_or_b64 exec, exec, s[0:1]
	v_lshlrev_b32_e32 v8, 16, v4
	v_and_b32_e32 v9, 0xffff0000, v4
	v_lshlrev_b32_e32 v10, 16, v5
	v_and_b32_e32 v11, 0xffff0000, v5
	v_pk_mul_f32 v[12:13], v[8:9], v[8:9]
	v_pk_mul_f32 v[14:15], v[10:11], v[10:11]
	v_add_f32_e32 v12, v12, v13
	v_lshlrev_b32_e32 v4, 16, v6
	v_and_b32_e32 v5, 0xffff0000, v6
	v_add_f32_e32 v12, v12, v14
	v_pk_mul_f32 v[26:27], v[4:5], v[4:5]
	v_add_f32_e32 v12, v15, v12
	v_lshlrev_b32_e32 v6, 16, v7
	v_and_b32_e32 v7, 0xffff0000, v7
	v_add_f32_e32 v12, v26, v12
	v_pk_mul_f32 v[28:29], v[6:7], v[6:7]
	v_add_f32_e32 v12, v27, v12
	v_add_f32_e32 v12, v28, v12
	v_add_f32_e32 v12, v29, v12
	s_nop 1
	v_cmp_gt_i32_e64 s[8:9], 10, v43
	v_cmp_gt_i32_e64 s[10:11], 8, v43
	v_cmp_lt_i32_e64 s[12:13], 7, v43
	s_and_b64 s[0:1], s[6:7], s[8:9]
	s_waitcnt lgkmcnt(0)
	v_add_f32_dpp v12, v12, v12 quad_perm:[1,0,3,2] row_mask:0xf bank_mask:0xf
	s_nop 1
	s_waitcnt lgkmcnt(0)
	v_add_f32_dpp v12, v12, v12 quad_perm:[2,3,0,1] row_mask:0xf bank_mask:0xf
	s_nop 1
	v_mov_b32_dpp v13, v12 row_shl:4 row_mask:0xf bank_mask:0x5
	v_mov_b32_dpp v13, v12 row_shr:4 row_mask:0xf bank_mask:0xa
	s_waitcnt lgkmcnt(0)
	v_add_f32_e32 v12, v12, v13
	s_nop 1
	v_mov_b32_dpp v13, v12 row_ror:8 row_mask:0xf bank_mask:0xf
	s_and_saveexec_b64 s[14:15], s[0:1]
	s_cbranch_execz .LBB0_319
	s_waitcnt lgkmcnt(0)
	v_add_f32_e32 v12, v12, v13
	v_fmamk_f32 v12, v12, 0x3c000000, v115
	v_cmp_gt_f32_e64 s[0:1], s78, v12
	v_mul_f32_e32 v13, 0x4b800000, v12
	v_mov_b32_e32 v14, s20
	v_cndmask_b32_e64 v12, v12, v13, s[0:1]
	v_rsq_f32_e32 v12, v12
	v_mov_b32_e32 v25, v113
	v_mul_f32_e32 v13, 0x45800000, v12
	v_cndmask_b32_e64 v30, v12, v13, s[0:1]
	v_mov_b32_e32 v12, s3
	v_mov_b32_e32 v13, s21
	v_cndmask_b32_e64 v13, v12, v13, s[10:11]
	v_mov_b32_e32 v12, s2
	v_cndmask_b32_e64 v12, v12, v14, s[10:11]
	v_lshl_add_u64 v[26:27], v[12:13], 0, v[24:25]
	v_mov_b32_e32 v12, v154
	v_mov_b32_e32 v13, v155
	v_mov_b32_e32 v14, v156
	v_mov_b32_e32 v15, v157
	v_mov_b32_e32 v26, v158
	v_mov_b32_e32 v27, v159
	v_mov_b32_e32 v28, v160
	v_mov_b32_e32 v29, v161
	v_pk_mul_f32 v[14:15], v[30:31], v[14:15] op_sel_hi:[0,1]
	v_pk_mul_f32 v[28:29], v[30:31], v[28:29] op_sel_hi:[0,1]
	v_pk_mul_f32 v[12:13], v[30:31], v[12:13] op_sel_hi:[0,1]
	v_pk_mul_f32 v[26:27], v[30:31], v[26:27] op_sel_hi:[0,1]
	v_pk_mul_f32 v[6:7], v[28:29], v[6:7]
	v_pk_mul_f32 v[10:11], v[14:15], v[10:11]
	v_pk_mul_f32 v[4:5], v[26:27], v[4:5]
	v_pk_mul_f32 v[8:9], v[12:13], v[8:9]
.LBB0_319:
	s_or_b64 exec, exec, s[14:15]
	s_nop 1
	v_mov_b32_dpp v30, v8 row_shl:4 row_mask:0xf bank_mask:0x5
	v_mov_b32_dpp v30, v8 row_shr:4 row_mask:0xf bank_mask:0xa
	s_nop 1
	v_mov_b32_dpp v31, v9 row_shl:4 row_mask:0xf bank_mask:0x5
	v_mov_b32_dpp v31, v9 row_shr:4 row_mask:0xf bank_mask:0xa
	s_nop 1
	v_mov_b32_dpp v28, v10 row_shl:4 row_mask:0xf bank_mask:0x5
	v_mov_b32_dpp v28, v10 row_shr:4 row_mask:0xf bank_mask:0xa
	s_nop 1
	v_mov_b32_dpp v29, v11 row_shl:4 row_mask:0xf bank_mask:0x5
	v_mov_b32_dpp v29, v11 row_shr:4 row_mask:0xf bank_mask:0xa
	s_nop 1
	v_mov_b32_dpp v26, v4 row_shl:4 row_mask:0xf bank_mask:0x5
	v_mov_b32_dpp v26, v4 row_shr:4 row_mask:0xf bank_mask:0xa
	s_nop 1
	v_mov_b32_dpp v27, v5 row_shl:4 row_mask:0xf bank_mask:0x5
	v_mov_b32_dpp v27, v5 row_shr:4 row_mask:0xf bank_mask:0xa
	s_nop 1
	v_mov_b32_dpp v25, v6 row_shl:4 row_mask:0xf bank_mask:0x5
	v_mov_b32_dpp v25, v6 row_shr:4 row_mask:0xf bank_mask:0xa
	s_nop 1
	v_mov_b32_dpp v15, v7 row_shl:4 row_mask:0xf bank_mask:0x5
	v_mov_b32_dpp v15, v7 row_shr:4 row_mask:0xf bank_mask:0xa
	v_and_b32_e32 v14, s55, v44
	s_and_b64 s[14:15], vcc, s[8:9]
	v_lshlrev_b32_e32 v12, 9, v14
	s_and_saveexec_b64 s[0:1], s[14:15]
	s_cbranch_execz .LBB0_321
	s_waitcnt lgkmcnt(0)
	v_mov_b32_e32 v13, v113
	v_lshl_add_u64 v[54:55], v[20:21], 0, v[12:13]
	v_mov_b32_e32 v32, v162
	v_mov_b32_e32 v33, v163
	v_mov_b32_e32 v34, v164
	v_mov_b32_e32 v35, v165
	v_mov_b32_e32 v46, v166
	v_mov_b32_e32 v47, v167
	v_mov_b32_e32 v48, v168
	v_mov_b32_e32 v49, v169
	v_mov_b32_e32 v50, v170
	v_mov_b32_e32 v51, v171
	v_mov_b32_e32 v52, v172
	v_mov_b32_e32 v53, v173
	v_mov_b32_e32 v54, v174
	v_mov_b32_e32 v55, v175
	v_mov_b32_e32 v56, v176
	v_mov_b32_e32 v57, v177
	v_pk_mul_f32 v[30:31], v[18:19], v[30:31]
	v_pk_mul_f32 v[28:29], v[18:19], v[28:29]
	v_pk_mul_f32 v[26:27], v[18:19], v[26:27]
	v_mul_f32_e32 v13, v18, v25
	s_nop 0
	v_mul_f32_e32 v6, v6, v32
	v_mul_f32_e32 v32, v13, v33
	v_mov_b32_e32 v58, v54
	v_mov_b32_e32 v59, v56
	v_mov_b32_e32 v56, v55
	v_mov_b32_e32 v54, v50
	v_mov_b32_e32 v55, v52
	v_mov_b32_e32 v52, v51
	v_mov_b32_e32 v50, v46
	v_mov_b32_e32 v51, v48
	v_mov_b32_e32 v48, v47
	v_mul_f32_e32 v47, v18, v15
	v_mov_b32_e32 v46, v7
	v_pk_mul_f32 v[34:35], v[46:47], v[34:35]
	v_pk_mul_f32 v[30:31], v[30:31], v[56:57]
	v_pk_mul_f32 v[28:29], v[28:29], v[52:53]
	v_pk_mul_f32 v[26:27], v[26:27], v[48:49]
	v_mov_b32_e32 v7, v34
	v_mov_b32_e32 v33, v35
	v_pk_fma_f32 v[8:9], v[8:9], v[58:59], v[30:31]
	v_pk_fma_f32 v[10:11], v[10:11], v[54:55], v[28:29]
	v_pk_fma_f32 v[4:5], v[4:5], v[50:51], v[26:27]
	v_pk_add_f32 v[6:7], v[6:7], v[32:33]

.LBB0_333:
	s_or_b64 exec, exec, s[0:1]
	s_nop 0
	v_lshlrev_b32_e32 v4, 16, v0
	v_and_b32_e32 v5, 0xffff0000, v0
	v_lshlrev_b32_e32 v6, 16, v1
	v_and_b32_e32 v7, 0xffff0000, v1
	v_pk_mul_f32 v[8:9], v[4:5], v[4:5]
	v_pk_mul_f32 v[10:11], v[6:7], v[6:7]
	v_add_f32_e32 v8, v8, v9
	v_lshlrev_b32_e32 v0, 16, v2
	v_and_b32_e32 v1, 0xffff0000, v2
	v_add_f32_e32 v8, v8, v10
	v_pk_mul_f32 v[12:13], v[0:1], v[0:1]
	v_add_f32_e32 v8, v11, v8
	v_lshlrev_b32_e32 v2, 16, v3
	v_and_b32_e32 v3, 0xffff0000, v3
	v_add_f32_e32 v8, v12, v8
	v_pk_mul_f32 v[14:15], v[2:3], v[2:3]
	v_add_f32_e32 v8, v13, v8
	v_add_f32_e32 v8, v14, v8
	v_add_f32_e32 v8, v15, v8
	s_nop 1
	v_cmp_gt_i32_e64 s[6:7], 10, v41
	v_cmp_gt_i32_e64 s[8:9], 8, v41
	v_cmp_lt_i32_e64 s[10:11], 7, v41
	s_and_b64 s[0:1], s[4:5], s[6:7]
	s_waitcnt lgkmcnt(0)
	v_add_f32_dpp v8, v8, v8 quad_perm:[1,0,3,2] row_mask:0xf bank_mask:0xf
	s_nop 1
	s_waitcnt lgkmcnt(0)
	v_add_f32_dpp v8, v8, v8 quad_perm:[2,3,0,1] row_mask:0xf bank_mask:0xf
	s_nop 1
	v_mov_b32_dpp v9, v8 row_shl:4 row_mask:0xf bank_mask:0x5
	v_mov_b32_dpp v9, v8 row_shr:4 row_mask:0xf bank_mask:0xa
	s_waitcnt lgkmcnt(0)
	v_add_f32_e32 v8, v8, v9
	s_nop 1
	v_mov_b32_dpp v9, v8 row_ror:8 row_mask:0xf bank_mask:0xf
	s_and_saveexec_b64 s[12:13], s[0:1]
	s_cbranch_execz .LBB0_335
	s_waitcnt lgkmcnt(0)
	v_add_f32_e32 v8, v8, v9
	v_fmamk_f32 v8, v8, 0x3c000000, v115
	v_cmp_gt_f32_e64 s[0:1], s78, v8
	v_mul_f32_e32 v9, 0x4b800000, v8
	v_mov_b32_e32 v10, s20
	v_cndmask_b32_e64 v8, v8, v9, s[0:1]
	v_rsq_f32_e32 v8, v8
	v_mov_b32_e32 v25, v113
	v_mul_f32_e32 v9, 0x45800000, v8
	v_cndmask_b32_e64 v26, v8, v9, s[0:1]
	v_mov_b32_e32 v8, s3
	v_mov_b32_e32 v9, s21
	v_cndmask_b32_e64 v9, v8, v9, s[8:9]
	v_mov_b32_e32 v8, s2
	v_cndmask_b32_e64 v8, v8, v10, s[8:9]
	v_lshl_add_u64 v[12:13], v[8:9], 0, v[24:25]
	v_mov_b32_e32 v8, v182
	v_mov_b32_e32 v9, v183
	v_mov_b32_e32 v10, v184
	v_mov_b32_e32 v11, v185
	v_mov_b32_e32 v12, v186
	v_mov_b32_e32 v13, v187
	v_mov_b32_e32 v14, v188
	v_mov_b32_e32 v15, v189
	v_pk_mul_f32 v[10:11], v[26:27], v[10:11] op_sel_hi:[0,1]
	v_pk_mul_f32 v[14:15], v[26:27], v[14:15] op_sel_hi:[0,1]
	v_pk_mul_f32 v[8:9], v[26:27], v[8:9] op_sel_hi:[0,1]
	v_pk_mul_f32 v[12:13], v[26:27], v[12:13] op_sel_hi:[0,1]
	v_pk_mul_f32 v[2:3], v[14:15], v[2:3]
	v_pk_mul_f32 v[6:7], v[10:11], v[6:7]
	v_pk_mul_f32 v[0:1], v[12:13], v[0:1]
	v_pk_mul_f32 v[4:5], v[8:9], v[4:5]
.LBB0_335:
	s_or_b64 exec, exec, s[12:13]
	s_nop 1
	v_mov_b32_dpp v26, v4 row_shl:4 row_mask:0xf bank_mask:0x5
	v_mov_b32_dpp v26, v4 row_shr:4 row_mask:0xf bank_mask:0xa
	s_nop 1
	v_mov_b32_dpp v27, v5 row_shl:4 row_mask:0xf bank_mask:0x5
	v_mov_b32_dpp v27, v5 row_shr:4 row_mask:0xf bank_mask:0xa
	s_nop 1
	v_mov_b32_dpp v14, v6 row_shl:4 row_mask:0xf bank_mask:0x5
	v_mov_b32_dpp v14, v6 row_shr:4 row_mask:0xf bank_mask:0xa
	s_nop 1
	v_mov_b32_dpp v15, v7 row_shl:4 row_mask:0xf bank_mask:0x5
	v_mov_b32_dpp v15, v7 row_shr:4 row_mask:0xf bank_mask:0xa
	s_nop 1
	v_mov_b32_dpp v12, v0 row_shl:4 row_mask:0xf bank_mask:0x5
	v_mov_b32_dpp v12, v0 row_shr:4 row_mask:0xf bank_mask:0xa
	s_nop 1
	v_mov_b32_dpp v13, v1 row_shl:4 row_mask:0xf bank_mask:0x5
	v_mov_b32_dpp v13, v1 row_shr:4 row_mask:0xf bank_mask:0xa
	s_nop 1
	v_mov_b32_dpp v25, v2 row_shl:4 row_mask:0xf bank_mask:0x5
	v_mov_b32_dpp v25, v2 row_shr:4 row_mask:0xf bank_mask:0xa
	s_nop 1
	v_mov_b32_dpp v11, v3 row_shl:4 row_mask:0xf bank_mask:0x5
	v_mov_b32_dpp v11, v3 row_shr:4 row_mask:0xf bank_mask:0xa
	v_and_b32_e32 v10, s55, v42
	s_and_b64 s[12:13], vcc, s[6:7]
	v_lshlrev_b32_e32 v8, 9, v10
	s_and_saveexec_b64 s[0:1], s[12:13]
	s_cbranch_execz .LBB0_337
	s_waitcnt lgkmcnt(0)
	v_mov_b32_e32 v9, v113
	v_lshl_add_u64 v[48:49], v[20:21], 0, v[8:9]
	v_mov_b32_e32 v28, v190
	v_mov_b32_e32 v29, v191
	v_mov_b32_e32 v30, v192
	v_mov_b32_e32 v31, v193
	v_mov_b32_e32 v32, v194
	v_mov_b32_e32 v33, v195
	v_mov_b32_e32 v34, v196
	v_mov_b32_e32 v35, v197
	v_mov_b32_e32 v44, v198
	v_mov_b32_e32 v45, v199
	v_mov_b32_e32 v46, v200
	v_mov_b32_e32 v47, v201
	v_mov_b32_e32 v48, v202
	v_mov_b32_e32 v49, v203
	v_mov_b32_e32 v50, v204
	v_mov_b32_e32 v51, v205
	v_pk_mul_f32 v[26:27], v[18:19], v[26:27]
	v_pk_mul_f32 v[14:15], v[18:19], v[14:15]
	v_pk_mul_f32 v[12:13], v[18:19], v[12:13]
	v_mul_f32_e32 v9, v18, v25
	s_nop 0
	v_mul_f32_e32 v2, v2, v28
	v_mul_f32_e32 v28, v9, v29
	v_mov_b32_e32 v52, v48
	v_mov_b32_e32 v53, v50
	v_mov_b32_e32 v50, v49
	v_mov_b32_e32 v48, v44
	v_mov_b32_e32 v49, v46
	v_mov_b32_e32 v46, v45
	v_mov_b32_e32 v44, v32
	v_mov_b32_e32 v45, v34
	v_mov_b32_e32 v34, v33
	v_mul_f32_e32 v33, v18, v11
	v_mov_b32_e32 v32, v3
	v_pk_mul_f32 v[30:31], v[32:33], v[30:31]
	v_pk_mul_f32 v[26:27], v[26:27], v[50:51]
	v_pk_mul_f32 v[14:15], v[14:15], v[46:47]
	v_pk_mul_f32 v[12:13], v[12:13], v[34:35]
	v_mov_b32_e32 v3, v30
	v_mov_b32_e32 v29, v31
	v_pk_fma_f32 v[4:5], v[4:5], v[52:53], v[26:27]
	v_pk_fma_f32 v[6:7], v[6:7], v[48:49], v[14:15]
	v_pk_fma_f32 v[0:1], v[0:1], v[44:45], v[12:13]
	v_pk_add_f32 v[2:3], v[2:3], v[28:29]

.Lprepb_norope2:
	s_waitcnt vmcnt(0)
	v_lshlrev_b32_e32 v8, 16, v12
	v_and_b32_e32 v9, 0xffff0000, v12
	v_lshlrev_b32_e32 v10, 16, v13
	v_and_b32_e32 v11, 0xffff0000, v13
	v_pk_mul_f32 v[24:25], v[8:9], v[8:9]
	v_pk_mul_f32 v[26:27], v[10:11], v[10:11]
	v_add_f32_e32 v24, v24, v25
	v_lshlrev_b32_e32 v12, 16, v14
	v_and_b32_e32 v13, 0xffff0000, v14
	v_add_f32_e32 v24, v24, v26
	v_pk_mul_f32 v[30:31], v[12:13], v[12:13]
	v_add_f32_e32 v24, v27, v24
	v_lshlrev_b32_e32 v14, 16, v15
	v_and_b32_e32 v15, 0xffff0000, v15
	v_add_f32_e32 v24, v30, v24
	v_pk_mul_f32 v[32:33], v[14:15], v[14:15]
	v_add_f32_e32 v24, v31, v24
	v_add_f32_e32 v24, v32, v24
	v_add_f32_e32 v24, v33, v24
	s_nop 1
	s_waitcnt lgkmcnt(0)
	v_add_f32_dpp v24, v24, v24 quad_perm:[1,0,3,2] row_mask:0xf bank_mask:0xf
	s_nop 1
	s_waitcnt lgkmcnt(0)
	v_add_f32_dpp v24, v24, v24 quad_perm:[2,3,0,1] row_mask:0xf bank_mask:0xf
	s_nop 1
	v_mov_b32_dpp v25, v24 row_shl:4 row_mask:0xf bank_mask:0x5
	v_mov_b32_dpp v25, v24 row_shr:4 row_mask:0xf bank_mask:0xa
	s_waitcnt lgkmcnt(0)
	v_add_f32_e32 v25, v24, v25
	s_nop 1
	v_mov_b32_dpp v26, v25 row_ror:8 row_mask:0xf bank_mask:0xf
	v_lshlrev_b32_e32 v24, 2, v16
	s_and_saveexec_b64 s[58:59], s[0:1]
	s_cbranch_execz .LBB0_1013
	s_waitcnt lgkmcnt(0)
	v_add_f32_e32 v25, v25, v26
	v_fmamk_f32 v25, v25, 0x3c000000, v115
	v_cmp_gt_f32_e64 s[0:1], s67, v25
	v_mul_f32_e32 v26, 0x4b800000, v25
	v_mov_b32_e32 v27, s35
	v_cndmask_b32_e64 v25, v25, v26, s[0:1]
	v_rsq_f32_e32 v25, v25
	s_nop 0
	v_mul_f32_e32 v26, 0x45800000, v25
	v_cndmask_b32_e64 v26, v25, v26, s[0:1]
	v_mov_b32_e32 v25, s3
	v_cndmask_b32_e64 v31, v25, v27, s[12:13]
	v_mov_b32_e32 v25, s2
	v_mov_b32_e32 v27, s34
	v_cndmask_b32_e64 v30, v25, v27, s[12:13]
	v_mov_b32_e32 v25, v113
	v_lshl_add_u64 v[34:35], v[30:31], 0, v[24:25]
	v_mov_b32_e32 v30, v130
	v_mov_b32_e32 v31, v131
	v_mov_b32_e32 v32, v132
	v_mov_b32_e32 v33, v133
	v_mov_b32_e32 v48, v134
	v_mov_b32_e32 v49, v135
	v_mov_b32_e32 v50, v136
	v_mov_b32_e32 v51, v137
	v_pk_mul_f32 v[32:33], v[26:27], v[32:33] op_sel_hi:[0,1]
	v_pk_mul_f32 v[34:35], v[26:27], v[50:51] op_sel_hi:[0,1]
	v_pk_mul_f32 v[30:31], v[26:27], v[30:31] op_sel_hi:[0,1]
	v_pk_mul_f32 v[26:27], v[26:27], v[48:49] op_sel_hi:[0,1]
	v_pk_mul_f32 v[14:15], v[34:35], v[14:15]
	v_pk_mul_f32 v[10:11], v[32:33], v[10:11]
	v_pk_mul_f32 v[12:13], v[26:27], v[12:13]
	v_pk_mul_f32 v[8:9], v[30:31], v[8:9]
.LBB0_1013:
	s_or_b64 exec, exec, s[58:59]
	s_nop 1
	v_mov_b32_dpp v34, v8 row_shl:4 row_mask:0xf bank_mask:0x5
	v_mov_b32_dpp v34, v8 row_shr:4 row_mask:0xf bank_mask:0xa
	s_nop 1
	v_mov_b32_dpp v35, v9 row_shl:4 row_mask:0xf bank_mask:0x5
	v_mov_b32_dpp v35, v9 row_shr:4 row_mask:0xf bank_mask:0xa
	s_nop 1
	v_mov_b32_dpp v32, v10 row_shl:4 row_mask:0xf bank_mask:0x5
	v_mov_b32_dpp v32, v10 row_shr:4 row_mask:0xf bank_mask:0xa
	s_nop 1
	v_mov_b32_dpp v33, v11 row_shl:4 row_mask:0xf bank_mask:0x5
	v_mov_b32_dpp v33, v11 row_shr:4 row_mask:0xf bank_mask:0xa
	s_nop 1
	v_mov_b32_dpp v30, v12 row_shl:4 row_mask:0xf bank_mask:0x5
	v_mov_b32_dpp v30, v12 row_shr:4 row_mask:0xf bank_mask:0xa
	s_nop 1
	v_mov_b32_dpp v31, v13 row_shl:4 row_mask:0xf bank_mask:0x5
	v_mov_b32_dpp v31, v13 row_shr:4 row_mask:0xf bank_mask:0xa
	s_nop 1
	v_mov_b32_dpp v48, v14 row_shl:4 row_mask:0xf bank_mask:0x5
	v_mov_b32_dpp v48, v14 row_shr:4 row_mask:0xf bank_mask:0xa
	s_nop 1
	v_mov_b32_dpp v25, v15 row_shl:4 row_mask:0xf bank_mask:0x5
	v_mov_b32_dpp v25, v15 row_shr:4 row_mask:0xf bank_mask:0xa
	v_and_b32_e32 v28, s56, v47
	s_and_b64 s[58:59], vcc, s[10:11]
	s_waitcnt lgkmcnt(8)
	v_lshlrev_b32_e32 v26, 9, v28
	s_and_saveexec_b64 s[0:1], s[58:59]
	s_cbranch_execz .LBB0_1015
	v_mov_b32_e32 v27, v113
	v_lshl_add_u64 v[62:63], v[20:21], 0, v[26:27]
	v_mov_b32_e32 v50, v138
	v_mov_b32_e32 v51, v139
	v_mov_b32_e32 v52, v140
	v_mov_b32_e32 v53, v141
	v_mov_b32_e32 v54, v142
	v_mov_b32_e32 v55, v143
	v_mov_b32_e32 v56, v144
	v_mov_b32_e32 v57, v145
	v_mov_b32_e32 v58, v146
	v_mov_b32_e32 v59, v147
	v_mov_b32_e32 v60, v148
	v_mov_b32_e32 v61, v149
	v_mov_b32_e32 v62, v150
	v_mov_b32_e32 v63, v151
	v_mov_b32_e32 v64, v152
	v_mov_b32_e32 v65, v153
	s_waitcnt lgkmcnt(1)
	v_mul_f32_e32 v27, v18, v48
	v_pk_mul_f32 v[34:35], v[18:19], v[34:35]
	v_pk_mul_f32 v[32:33], v[18:19], v[32:33]
	v_pk_mul_f32 v[30:31], v[18:19], v[30:31]
	s_nop 0
	v_mul_f32_e32 v14, v14, v50
	v_mul_f32_e32 v48, v27, v51
	s_waitcnt lgkmcnt(0)
	v_mul_f32_e32 v51, v18, v25
	v_mov_b32_e32 v50, v15
	s_nop 0
	v_mov_b32_e32 v67, v64
	v_mov_b32_e32 v64, v63
	v_mov_b32_e32 v63, v60
	v_mov_b32_e32 v60, v59
	v_mov_b32_e32 v59, v56
	v_mov_b32_e32 v56, v55
	v_pk_mul_f32 v[50:51], v[50:51], v[52:53]
	v_mov_b32_e32 v66, v62
	v_pk_mul_f32 v[34:35], v[34:35], v[64:65]
	v_mov_b32_e32 v62, v58
	v_pk_mul_f32 v[32:33], v[32:33], v[60:61]
	v_mov_b32_e32 v58, v54
	v_pk_mul_f32 v[30:31], v[30:31], v[56:57]
	v_mov_b32_e32 v15, v50
	v_mov_b32_e32 v49, v51
	v_pk_fma_f32 v[8:9], v[8:9], v[66:67], v[34:35]
	v_pk_fma_f32 v[10:11], v[10:11], v[62:63], v[32:33]
	v_pk_fma_f32 v[12:13], v[12:13], v[58:59], v[30:31]
	v_pk_add_f32 v[14:15], v[14:15], v[48:49]

.LBB0_1027:
	s_or_b64 exec, exec, s[0:1]
	v_lshlrev_b32_e32 v8, 16, v4
	v_and_b32_e32 v9, 0xffff0000, v4
	v_lshlrev_b32_e32 v10, 16, v5
	v_and_b32_e32 v11, 0xffff0000, v5
	v_pk_mul_f32 v[12:13], v[8:9], v[8:9]
	v_pk_mul_f32 v[14:15], v[10:11], v[10:11]
	v_add_f32_e32 v12, v12, v13
	v_lshlrev_b32_e32 v4, 16, v6
	v_and_b32_e32 v5, 0xffff0000, v6
	v_add_f32_e32 v12, v12, v14
	v_pk_mul_f32 v[26:27], v[4:5], v[4:5]
	v_add_f32_e32 v12, v15, v12
	v_lshlrev_b32_e32 v6, 16, v7
	v_and_b32_e32 v7, 0xffff0000, v7
	v_add_f32_e32 v12, v26, v12
	v_pk_mul_f32 v[28:29], v[6:7], v[6:7]
	v_add_f32_e32 v12, v27, v12
	v_add_f32_e32 v12, v28, v12
	v_add_f32_e32 v12, v29, v12
	s_nop 1
	v_cmp_gt_i32_e64 s[8:9], 10, v44
	v_cmp_gt_i32_e64 s[10:11], 8, v44
	v_cmp_lt_i32_e64 s[12:13], 7, v44
	s_and_b64 s[0:1], s[6:7], s[8:9]
	s_waitcnt lgkmcnt(0)
	v_add_f32_dpp v12, v12, v12 quad_perm:[1,0,3,2] row_mask:0xf bank_mask:0xf
	s_nop 1
	s_waitcnt lgkmcnt(0)
	v_add_f32_dpp v12, v12, v12 quad_perm:[2,3,0,1] row_mask:0xf bank_mask:0xf
	s_nop 1
	v_mov_b32_dpp v13, v12 row_shl:4 row_mask:0xf bank_mask:0x5
	v_mov_b32_dpp v13, v12 row_shr:4 row_mask:0xf bank_mask:0xa
	s_waitcnt lgkmcnt(0)
	v_add_f32_e32 v12, v12, v13
	s_nop 1
	v_mov_b32_dpp v13, v12 row_ror:8 row_mask:0xf bank_mask:0xf
	s_and_saveexec_b64 s[14:15], s[0:1]
	s_cbranch_execz .LBB0_1029
	s_waitcnt lgkmcnt(0)
	v_add_f32_e32 v12, v12, v13
	v_fmamk_f32 v12, v12, 0x3c000000, v115
	v_cmp_gt_f32_e64 s[0:1], s67, v12
	v_mul_f32_e32 v13, 0x4b800000, v12
	v_mov_b32_e32 v14, s34
	v_cndmask_b32_e64 v12, v12, v13, s[0:1]
	v_rsq_f32_e32 v12, v12
	v_mov_b32_e32 v25, v113
	v_mul_f32_e32 v13, 0x45800000, v12
	v_cndmask_b32_e64 v30, v12, v13, s[0:1]
	v_mov_b32_e32 v12, s3
	v_mov_b32_e32 v13, s35
	v_cndmask_b32_e64 v13, v12, v13, s[10:11]
	v_mov_b32_e32 v12, s2
	v_cndmask_b32_e64 v12, v12, v14, s[10:11]
	v_lshl_add_u64 v[26:27], v[12:13], 0, v[24:25]
	v_mov_b32_e32 v12, v154
	v_mov_b32_e32 v13, v155
	v_mov_b32_e32 v14, v156
	v_mov_b32_e32 v15, v157
	v_mov_b32_e32 v26, v158
	v_mov_b32_e32 v27, v159
	v_mov_b32_e32 v28, v160
	v_mov_b32_e32 v29, v161
	v_pk_mul_f32 v[14:15], v[30:31], v[14:15] op_sel_hi:[0,1]
	v_pk_mul_f32 v[28:29], v[30:31], v[28:29] op_sel_hi:[0,1]
	v_pk_mul_f32 v[12:13], v[30:31], v[12:13] op_sel_hi:[0,1]
	v_pk_mul_f32 v[26:27], v[30:31], v[26:27] op_sel_hi:[0,1]
	v_pk_mul_f32 v[6:7], v[28:29], v[6:7]
	v_pk_mul_f32 v[10:11], v[14:15], v[10:11]
	v_pk_mul_f32 v[4:5], v[26:27], v[4:5]
	v_pk_mul_f32 v[8:9], v[12:13], v[8:9]
.LBB0_1029:
	s_or_b64 exec, exec, s[14:15]
	s_nop 1
	v_mov_b32_dpp v30, v8 row_shl:4 row_mask:0xf bank_mask:0x5
	v_mov_b32_dpp v30, v8 row_shr:4 row_mask:0xf bank_mask:0xa
	s_nop 1
	v_mov_b32_dpp v31, v9 row_shl:4 row_mask:0xf bank_mask:0x5
	v_mov_b32_dpp v31, v9 row_shr:4 row_mask:0xf bank_mask:0xa
	s_nop 1
	v_mov_b32_dpp v28, v10 row_shl:4 row_mask:0xf bank_mask:0x5
	v_mov_b32_dpp v28, v10 row_shr:4 row_mask:0xf bank_mask:0xa
	s_nop 1
	v_mov_b32_dpp v29, v11 row_shl:4 row_mask:0xf bank_mask:0x5
	v_mov_b32_dpp v29, v11 row_shr:4 row_mask:0xf bank_mask:0xa
	s_nop 1
	v_mov_b32_dpp v26, v4 row_shl:4 row_mask:0xf bank_mask:0x5
	v_mov_b32_dpp v26, v4 row_shr:4 row_mask:0xf bank_mask:0xa
	s_nop 1
	v_mov_b32_dpp v27, v5 row_shl:4 row_mask:0xf bank_mask:0x5
	v_mov_b32_dpp v27, v5 row_shr:4 row_mask:0xf bank_mask:0xa
	s_nop 1
	v_mov_b32_dpp v25, v6 row_shl:4 row_mask:0xf bank_mask:0x5
	v_mov_b32_dpp v25, v6 row_shr:4 row_mask:0xf bank_mask:0xa
	s_nop 1
	v_mov_b32_dpp v15, v7 row_shl:4 row_mask:0xf bank_mask:0x5
	v_mov_b32_dpp v15, v7 row_shr:4 row_mask:0xf bank_mask:0xa
	v_and_b32_e32 v14, s56, v45
	s_and_b64 s[14:15], vcc, s[8:9]
	v_lshlrev_b32_e32 v12, 9, v14
	s_and_saveexec_b64 s[0:1], s[14:15]
	s_cbranch_execz .LBB0_1031
	s_waitcnt lgkmcnt(0)
	v_mov_b32_e32 v13, v113
	v_lshl_add_u64 v[54:55], v[20:21], 0, v[12:13]
	v_mov_b32_e32 v32, v162
	v_mov_b32_e32 v33, v163
	v_mov_b32_e32 v34, v164
	v_mov_b32_e32 v35, v165
	v_mov_b32_e32 v46, v166
	v_mov_b32_e32 v47, v167
	v_mov_b32_e32 v48, v168
	v_mov_b32_e32 v49, v169
	v_mov_b32_e32 v50, v170
	v_mov_b32_e32 v51, v171
	v_mov_b32_e32 v52, v172
	v_mov_b32_e32 v53, v173
	v_mov_b32_e32 v54, v174
	v_mov_b32_e32 v55, v175
	v_mov_b32_e32 v56, v176
	v_mov_b32_e32 v57, v177
	v_pk_mul_f32 v[30:31], v[18:19], v[30:31]
	v_pk_mul_f32 v[28:29], v[18:19], v[28:29]
	v_pk_mul_f32 v[26:27], v[18:19], v[26:27]
	v_mul_f32_e32 v13, v18, v25
	s_nop 0
	v_mul_f32_e32 v6, v6, v32
	v_mul_f32_e32 v32, v13, v33
	v_mov_b32_e32 v58, v54
	v_mov_b32_e32 v59, v56
	v_mov_b32_e32 v56, v55
	v_mov_b32_e32 v54, v50
	v_mov_b32_e32 v55, v52
	v_mov_b32_e32 v52, v51
	v_mov_b32_e32 v50, v46
	v_mov_b32_e32 v51, v48
	v_mov_b32_e32 v48, v47
	v_mul_f32_e32 v47, v18, v15
	v_mov_b32_e32 v46, v7
	v_pk_mul_f32 v[34:35], v[46:47], v[34:35]
	v_pk_mul_f32 v[30:31], v[30:31], v[56:57]
	v_pk_mul_f32 v[28:29], v[28:29], v[52:53]
	v_pk_mul_f32 v[26:27], v[26:27], v[48:49]
	v_mov_b32_e32 v7, v34
	v_mov_b32_e32 v33, v35
	v_pk_fma_f32 v[8:9], v[8:9], v[58:59], v[30:31]
	v_pk_fma_f32 v[10:11], v[10:11], v[54:55], v[28:29]
	v_pk_fma_f32 v[4:5], v[4:5], v[50:51], v[26:27]
	v_pk_add_f32 v[6:7], v[6:7], v[32:33]

.LBB0_1043:
	s_or_b64 exec, exec, s[0:1]
	s_nop 0
	v_lshlrev_b32_e32 v4, 16, v0
	v_and_b32_e32 v5, 0xffff0000, v0
	v_lshlrev_b32_e32 v6, 16, v1
	v_and_b32_e32 v7, 0xffff0000, v1
	v_pk_mul_f32 v[8:9], v[4:5], v[4:5]
	v_pk_mul_f32 v[10:11], v[6:7], v[6:7]
	v_add_f32_e32 v8, v8, v9
	v_lshlrev_b32_e32 v0, 16, v2
	v_and_b32_e32 v1, 0xffff0000, v2
	v_add_f32_e32 v8, v8, v10
	v_pk_mul_f32 v[12:13], v[0:1], v[0:1]
	v_add_f32_e32 v8, v11, v8
	v_lshlrev_b32_e32 v2, 16, v3
	v_and_b32_e32 v3, 0xffff0000, v3
	v_add_f32_e32 v8, v12, v8
	v_pk_mul_f32 v[14:15], v[2:3], v[2:3]
	v_add_f32_e32 v8, v13, v8
	v_add_f32_e32 v8, v14, v8
	v_add_f32_e32 v8, v15, v8
	s_nop 1
	v_cmp_gt_i32_e64 s[6:7], 10, v42
	v_cmp_gt_i32_e64 s[8:9], 8, v42
	v_cmp_lt_i32_e64 s[10:11], 7, v42
	s_and_b64 s[0:1], s[4:5], s[6:7]
	s_waitcnt lgkmcnt(0)
	v_add_f32_dpp v8, v8, v8 quad_perm:[1,0,3,2] row_mask:0xf bank_mask:0xf
	s_nop 1
	s_waitcnt lgkmcnt(0)
	v_add_f32_dpp v8, v8, v8 quad_perm:[2,3,0,1] row_mask:0xf bank_mask:0xf
	s_nop 1
	v_mov_b32_dpp v9, v8 row_shl:4 row_mask:0xf bank_mask:0x5
	v_mov_b32_dpp v9, v8 row_shr:4 row_mask:0xf bank_mask:0xa
	s_waitcnt lgkmcnt(0)
	v_add_f32_e32 v8, v8, v9
	s_nop 1
	v_mov_b32_dpp v9, v8 row_ror:8 row_mask:0xf bank_mask:0xf
	s_and_saveexec_b64 s[12:13], s[0:1]
	s_cbranch_execz .LBB0_1045
	s_waitcnt lgkmcnt(0)
	v_add_f32_e32 v8, v8, v9
	v_fmamk_f32 v8, v8, 0x3c000000, v115
	v_cmp_gt_f32_e64 s[0:1], s67, v8
	v_mul_f32_e32 v9, 0x4b800000, v8
	v_mov_b32_e32 v10, s34
	v_cndmask_b32_e64 v8, v8, v9, s[0:1]
	v_rsq_f32_e32 v8, v8
	v_mov_b32_e32 v25, v113
	v_mul_f32_e32 v9, 0x45800000, v8
	v_cndmask_b32_e64 v26, v8, v9, s[0:1]
	v_mov_b32_e32 v8, s3
	v_mov_b32_e32 v9, s35
	v_cndmask_b32_e64 v9, v8, v9, s[8:9]
	v_mov_b32_e32 v8, s2
	v_cndmask_b32_e64 v8, v8, v10, s[8:9]
	v_lshl_add_u64 v[12:13], v[8:9], 0, v[24:25]
	v_mov_b32_e32 v8, v182
	v_mov_b32_e32 v9, v183
	v_mov_b32_e32 v10, v184
	v_mov_b32_e32 v11, v185
	v_mov_b32_e32 v12, v186
	v_mov_b32_e32 v13, v187
	v_mov_b32_e32 v14, v188
	v_mov_b32_e32 v15, v189
	v_pk_mul_f32 v[10:11], v[26:27], v[10:11] op_sel_hi:[0,1]
	v_pk_mul_f32 v[14:15], v[26:27], v[14:15] op_sel_hi:[0,1]
	v_pk_mul_f32 v[8:9], v[26:27], v[8:9] op_sel_hi:[0,1]
	v_pk_mul_f32 v[12:13], v[26:27], v[12:13] op_sel_hi:[0,1]
	v_pk_mul_f32 v[2:3], v[14:15], v[2:3]
	v_pk_mul_f32 v[6:7], v[10:11], v[6:7]
	v_pk_mul_f32 v[0:1], v[12:13], v[0:1]
	v_pk_mul_f32 v[4:5], v[8:9], v[4:5]
.LBB0_1045:
	s_or_b64 exec, exec, s[12:13]
	s_nop 1
	v_mov_b32_dpp v26, v4 row_shl:4 row_mask:0xf bank_mask:0x5
	v_mov_b32_dpp v26, v4 row_shr:4 row_mask:0xf bank_mask:0xa
	s_nop 1
	v_mov_b32_dpp v27, v5 row_shl:4 row_mask:0xf bank_mask:0x5
	v_mov_b32_dpp v27, v5 row_shr:4 row_mask:0xf bank_mask:0xa
	s_nop 1
	v_mov_b32_dpp v14, v6 row_shl:4 row_mask:0xf bank_mask:0x5
	v_mov_b32_dpp v14, v6 row_shr:4 row_mask:0xf bank_mask:0xa
	s_nop 1
	v_mov_b32_dpp v15, v7 row_shl:4 row_mask:0xf bank_mask:0x5
	v_mov_b32_dpp v15, v7 row_shr:4 row_mask:0xf bank_mask:0xa
	s_nop 1
	v_mov_b32_dpp v12, v0 row_shl:4 row_mask:0xf bank_mask:0x5
	v_mov_b32_dpp v12, v0 row_shr:4 row_mask:0xf bank_mask:0xa
	s_nop 1
	v_mov_b32_dpp v13, v1 row_shl:4 row_mask:0xf bank_mask:0x5
	v_mov_b32_dpp v13, v1 row_shr:4 row_mask:0xf bank_mask:0xa
	s_nop 1
	v_mov_b32_dpp v25, v2 row_shl:4 row_mask:0xf bank_mask:0x5
	v_mov_b32_dpp v25, v2 row_shr:4 row_mask:0xf bank_mask:0xa
	s_nop 1
	v_mov_b32_dpp v11, v3 row_shl:4 row_mask:0xf bank_mask:0x5
	v_mov_b32_dpp v11, v3 row_shr:4 row_mask:0xf bank_mask:0xa
	v_and_b32_e32 v10, s56, v43
	s_and_b64 s[12:13], vcc, s[6:7]
	v_lshlrev_b32_e32 v8, 9, v10
	s_and_saveexec_b64 s[0:1], s[12:13]
	s_cbranch_execz .LBB0_1047
	s_waitcnt lgkmcnt(0)
	v_mov_b32_e32 v9, v113
	v_lshl_add_u64 v[48:49], v[20:21], 0, v[8:9]
	v_mov_b32_e32 v28, v190
	v_mov_b32_e32 v29, v191
	v_mov_b32_e32 v30, v192
	v_mov_b32_e32 v31, v193
	v_mov_b32_e32 v32, v194
	v_mov_b32_e32 v33, v195
	v_mov_b32_e32 v34, v196
	v_mov_b32_e32 v35, v197
	v_mov_b32_e32 v44, v198
	v_mov_b32_e32 v45, v199
	v_mov_b32_e32 v46, v200
	v_mov_b32_e32 v47, v201
	v_mov_b32_e32 v48, v202
	v_mov_b32_e32 v49, v203
	v_mov_b32_e32 v50, v204
	v_mov_b32_e32 v51, v205
	v_pk_mul_f32 v[26:27], v[18:19], v[26:27]
	v_pk_mul_f32 v[14:15], v[18:19], v[14:15]
	v_pk_mul_f32 v[12:13], v[18:19], v[12:13]
	v_mul_f32_e32 v9, v18, v25
	s_nop 0
	v_mul_f32_e32 v2, v2, v28
	v_mul_f32_e32 v28, v9, v29
	v_mov_b32_e32 v52, v48
	v_mov_b32_e32 v53, v50
	v_mov_b32_e32 v50, v49
	v_mov_b32_e32 v48, v44
	v_mov_b32_e32 v49, v46
	v_mov_b32_e32 v46, v45
	v_mov_b32_e32 v44, v32
	v_mov_b32_e32 v45, v34
	v_mov_b32_e32 v34, v33
	v_mul_f32_e32 v33, v18, v11
	v_mov_b32_e32 v32, v3
	v_pk_mul_f32 v[30:31], v[32:33], v[30:31]
	v_pk_mul_f32 v[26:27], v[26:27], v[50:51]
	v_pk_mul_f32 v[14:15], v[14:15], v[46:47]
	v_pk_mul_f32 v[12:13], v[12:13], v[34:35]
	v_mov_b32_e32 v3, v30
	v_mov_b32_e32 v29, v31
	v_pk_fma_f32 v[4:5], v[4:5], v[52:53], v[26:27]
	v_pk_fma_f32 v[6:7], v[6:7], v[48:49], v[14:15]
	v_pk_fma_f32 v[0:1], v[0:1], v[44:45], v[12:13]
	v_pk_add_f32 v[2:3], v[2:3], v[28:29]
